# EpiF32 bf16 epilogues of P2/P6/P10/P13: n=0/1 8-byte store pairs merged into 16-byte stores via v_permlane16_swap (32 -> 16 stores per tile, same bytes/addresses)
# speedup vs baseline: 1.0199x; 1.0199x over previous
; __device__ __forceinline__ unsigned pk2(float lo, float hi) { f32x2 v = {lo, hi}; bf16x2_t b = __builtin_convertvector(v, bf16x2_t); return __builtin_bit_cast(unsigned, b); }
;     __device__ __forceinline__ void operator()(const f32x4 (&acc)[2][2][4][2], const Unit& u, int wr, int wc, int fr, int fq) const {
;     ...
; #pragma unroll
;             for (int ai = 0; ai < 2; ++ai)
; #pragma unroll
;                 for (int m = 0; m < 4; ++m) { bf16_t* rowp = Cb + (size_t)(row0 + ai * HALF + m * 16) * ldc + col0;
; #pragma unroll
;                     for (int bj = 0; bj < 2; ++bj)
; #pragma unroll
;                         for (int n = 0; n < 2; ++n) { const f32x4 v = acc[ai][bj][m][n]; *(u32x2*)(rowp + bj * HALF + n * 16) = (u32x2){pk2(v[0], v[1]), pk2(v[2], v[3])}; } }
.LBB0_284:
	v_lshl_add_u32 v136, s45, 8, v143
	v_lshl_or_b32 v138, s44, 8, v145
	s_mov_b64 s[22:23], -1
	s_cmp_gt_i32 s4, -1
	v_ashrrev_i32_e32 v139, 31, v138
	v_ashrrev_i32_e32 v137, 31, v136
	s_cbranch_scc1 .LBB0_289
	v_readlane_b32 s22, v255, 16
	v_readlane_b32 s23, v255, 17
	v_lshlrev_b64 v[150:151], 12, v[136:137]
	v_lshlrev_b64 v[152:153], 1, v[138:139]
	s_nop 0
	v_lshl_add_u64 v[150:151], s[22:23], 0, v[150:151]
	v_lshl_add_u64 v[150:151], v[150:151], 0, v[152:153]
	v_and_b32_e32 v152, 4, v145
	v_mul_u32_u24_e32 v152, 6, v152
	v_mov_b32_e32 v153, 0
	v_lshl_add_u64 v[150:151], v[150:151], 0, v[152:153]
	v_cvt_pk_bf16_f32 v126, v126, v127
	v_cvt_pk_bf16_f32 v127, v128, v129
	v_cvt_pk_bf16_f32 v128, v122, v123
	v_cvt_pk_bf16_f32 v129, v124, v125
	v_cvt_pk_bf16_f32 v110, v110, v111
	v_cvt_pk_bf16_f32 v111, v112, v113
	v_cvt_pk_bf16_f32 v112, v106, v107
	v_cvt_pk_bf16_f32 v113, v108, v109
	v_cvt_pk_bf16_f32 v118, v118, v119
	v_cvt_pk_bf16_f32 v119, v120, v121
	v_cvt_pk_bf16_f32 v120, v114, v115
	v_cvt_pk_bf16_f32 v121, v116, v117
	v_cvt_pk_bf16_f32 v94, v94, v95
	v_cvt_pk_bf16_f32 v95, v96, v97
	v_cvt_pk_bf16_f32 v96, v90, v91
	v_cvt_pk_bf16_f32 v97, v92, v93
	v_cvt_pk_bf16_f32 v102, v102, v103
	v_cvt_pk_bf16_f32 v103, v104, v105
	v_cvt_pk_bf16_f32 v104, v98, v99
	v_cvt_pk_bf16_f32 v105, v100, v101
	v_cvt_pk_bf16_f32 v78, v78, v79
	v_cvt_pk_bf16_f32 v79, v80, v81
	v_cvt_pk_bf16_f32 v80, v74, v75
	v_cvt_pk_bf16_f32 v81, v76, v77
	v_cvt_pk_bf16_f32 v86, v86, v87
	v_cvt_pk_bf16_f32 v87, v88, v89
	v_cvt_pk_bf16_f32 v88, v82, v83
	v_cvt_pk_bf16_f32 v89, v84, v85
	v_cvt_pk_bf16_f32 v70, v70, v71
	v_cvt_pk_bf16_f32 v71, v72, v73
	v_cvt_pk_bf16_f32 v72, v66, v67
	v_cvt_pk_bf16_f32 v73, v68, v69
	v_cvt_pk_bf16_f32 v62, v62, v63
	v_cvt_pk_bf16_f32 v63, v64, v65
	v_cvt_pk_bf16_f32 v64, v58, v59
	v_cvt_pk_bf16_f32 v65, v60, v61
	v_cvt_pk_bf16_f32 v46, v46, v47
	v_cvt_pk_bf16_f32 v47, v48, v49
	v_cvt_pk_bf16_f32 v48, v42, v43
	v_cvt_pk_bf16_f32 v49, v44, v45
	v_cvt_pk_bf16_f32 v54, v54, v55
	v_cvt_pk_bf16_f32 v55, v56, v57
	v_cvt_pk_bf16_f32 v56, v50, v51
	v_cvt_pk_bf16_f32 v57, v52, v53
	v_cvt_pk_bf16_f32 v30, v30, v31
	v_cvt_pk_bf16_f32 v31, v32, v33
	v_cvt_pk_bf16_f32 v32, v26, v27
	v_cvt_pk_bf16_f32 v33, v28, v29
	v_cvt_pk_bf16_f32 v38, v38, v39
	v_cvt_pk_bf16_f32 v39, v40, v41
	v_cvt_pk_bf16_f32 v40, v34, v35
	v_cvt_pk_bf16_f32 v41, v36, v37
	v_cvt_pk_bf16_f32 v14, v14, v15
	v_cvt_pk_bf16_f32 v15, v16, v17
	v_cvt_pk_bf16_f32 v16, v10, v11
	v_cvt_pk_bf16_f32 v17, v12, v13
	v_cvt_pk_bf16_f32 v22, v22, v23
	v_cvt_pk_bf16_f32 v23, v24, v25
	v_cvt_pk_bf16_f32 v24, v18, v19
	v_cvt_pk_bf16_f32 v25, v20, v21
	v_cvt_pk_bf16_f32 v6, v6, v7
	v_cvt_pk_bf16_f32 v7, v8, v9
	v_cvt_pk_bf16_f32 v8, v2, v3
	v_cvt_pk_bf16_f32 v9, v4, v5
	s_nop 1
	v_permlane16_swap_b32_e32 v126, v128
	v_permlane16_swap_b32_e32 v127, v129
	v_permlane16_swap_b32_e32 v110, v112
	v_permlane16_swap_b32_e32 v111, v113
	v_permlane16_swap_b32_e32 v118, v120
	v_permlane16_swap_b32_e32 v119, v121
	v_permlane16_swap_b32_e32 v94, v96
	v_permlane16_swap_b32_e32 v95, v97
	v_permlane16_swap_b32_e32 v102, v104
	v_permlane16_swap_b32_e32 v103, v105
	v_permlane16_swap_b32_e32 v78, v80
	v_permlane16_swap_b32_e32 v79, v81
	v_permlane16_swap_b32_e32 v86, v88
	v_permlane16_swap_b32_e32 v87, v89
	v_permlane16_swap_b32_e32 v70, v72
	v_permlane16_swap_b32_e32 v71, v73
	v_permlane16_swap_b32_e32 v62, v64
	v_permlane16_swap_b32_e32 v63, v65
	v_permlane16_swap_b32_e32 v46, v48
	v_permlane16_swap_b32_e32 v47, v49
	v_permlane16_swap_b32_e32 v54, v56
	v_permlane16_swap_b32_e32 v55, v57
	v_permlane16_swap_b32_e32 v30, v32
	v_permlane16_swap_b32_e32 v31, v33
	v_permlane16_swap_b32_e32 v38, v40
	v_permlane16_swap_b32_e32 v39, v41
	v_permlane16_swap_b32_e32 v14, v16
	v_permlane16_swap_b32_e32 v15, v17
	v_permlane16_swap_b32_e32 v22, v24
	v_permlane16_swap_b32_e32 v23, v25
	v_permlane16_swap_b32_e32 v6, v8
	v_permlane16_swap_b32_e32 v7, v9
	s_mov_b64 s[22:23], 0x10000
	global_store_dwordx4 v[150:151], v[126:129], off
	global_store_dwordx4 v[150:151], v[110:113], off offset:256
	v_lshl_add_u64 v[150:151], v[150:151], 0, s[22:23]
	global_store_dwordx4 v[150:151], v[118:121], off
	global_store_dwordx4 v[150:151], v[94:97], off offset:256
	v_lshl_add_u64 v[150:151], v[150:151], 0, s[22:23]
	global_store_dwordx4 v[150:151], v[102:105], off
	global_store_dwordx4 v[150:151], v[78:81], off offset:256
	v_lshl_add_u64 v[150:151], v[150:151], 0, s[22:23]
	global_store_dwordx4 v[150:151], v[86:89], off
	global_store_dwordx4 v[150:151], v[70:73], off offset:256
	s_mov_b64 s[22:23], 0x50000
	v_lshl_add_u64 v[150:151], v[150:151], 0, s[22:23]
	s_mov_b64 s[22:23], 0x10000
	global_store_dwordx4 v[150:151], v[62:65], off
	global_store_dwordx4 v[150:151], v[46:49], off offset:256
	v_lshl_add_u64 v[150:151], v[150:151], 0, s[22:23]
	global_store_dwordx4 v[150:151], v[54:57], off
	global_store_dwordx4 v[150:151], v[30:33], off offset:256
	v_lshl_add_u64 v[150:151], v[150:151], 0, s[22:23]
	global_store_dwordx4 v[150:151], v[38:41], off
	global_store_dwordx4 v[150:151], v[14:17], off offset:256
	v_lshl_add_u64 v[150:151], v[150:151], 0, s[22:23]
	global_store_dwordx4 v[150:151], v[22:25], off
	global_store_dwordx4 v[150:151], v[6:9], off offset:256
	s_nop 1
	s_cbranch_execz .LBB0_290

; __device__ __forceinline__ unsigned pk2(float lo, float hi) { f32x2 v = {lo, hi}; bf16x2_t b = __builtin_convertvector(v, bf16x2_t); return __builtin_bit_cast(unsigned, b); }
;     __device__ __forceinline__ void operator()(const f32x4 (&acc)[2][2][4][2], const Unit& u, int wr, int wc, int fr, int fq) const {
;     ...
; #pragma unroll
;             for (int ai = 0; ai < 2; ++ai)
; #pragma unroll
;                 for (int m = 0; m < 4; ++m) { bf16_t* rowp = Cb + (size_t)(row0 + ai * HALF + m * 16) * ldc + col0;
; #pragma unroll
;                     for (int bj = 0; bj < 2; ++bj)
; #pragma unroll
;                         for (int n = 0; n < 2; ++n) { const f32x4 v = acc[ai][bj][m][n]; *(u32x2*)(rowp + bj * HALF + n * 16) = (u32x2){pk2(v[0], v[1]), pk2(v[2], v[3])}; } }
.LBB0_895:
	v_lshl_add_u32 v136, s14, 8, v140
	v_lshl_or_b32 v138, s12, 8, v142
	s_cmp_gt_i32 s0, -1
	s_mov_b64 s[12:13], -1
	s_cbranch_scc1 .LBB0_898
	v_ashrrev_i32_e32 v137, 31, v136
	v_readlane_b32 s12, v255, 16
	v_ashrrev_i32_e32 v139, 31, v138
	v_readlane_b32 s13, v255, 17
	v_lshlrev_b64 v[146:147], 12, v[136:137]
	v_lshlrev_b64 v[148:149], 1, v[138:139]
	s_nop 0
	v_lshl_add_u64 v[146:147], s[12:13], 0, v[146:147]
	v_lshl_add_u64 v[146:147], v[146:147], 0, v[148:149]
	v_and_b32_e32 v148, 4, v142
	v_mul_u32_u24_e32 v148, 6, v148
	v_mov_b32_e32 v149, 0
	v_lshl_add_u64 v[146:147], v[146:147], 0, v[148:149]
	v_cvt_pk_bf16_f32 v126, v126, v127
	v_cvt_pk_bf16_f32 v127, v128, v129
	v_cvt_pk_bf16_f32 v128, v122, v123
	v_cvt_pk_bf16_f32 v129, v124, v125
	v_cvt_pk_bf16_f32 v110, v110, v111
	v_cvt_pk_bf16_f32 v111, v112, v113
	v_cvt_pk_bf16_f32 v112, v106, v107
	v_cvt_pk_bf16_f32 v113, v108, v109
	v_cvt_pk_bf16_f32 v118, v118, v119
	v_cvt_pk_bf16_f32 v119, v120, v121
	v_cvt_pk_bf16_f32 v120, v114, v115
	v_cvt_pk_bf16_f32 v121, v116, v117
	v_cvt_pk_bf16_f32 v94, v94, v95
	v_cvt_pk_bf16_f32 v95, v96, v97
	v_cvt_pk_bf16_f32 v96, v90, v91
	v_cvt_pk_bf16_f32 v97, v92, v93
	v_cvt_pk_bf16_f32 v102, v102, v103
	v_cvt_pk_bf16_f32 v103, v104, v105
	v_cvt_pk_bf16_f32 v104, v98, v99
	v_cvt_pk_bf16_f32 v105, v100, v101
	v_cvt_pk_bf16_f32 v78, v78, v79
	v_cvt_pk_bf16_f32 v79, v80, v81
	v_cvt_pk_bf16_f32 v80, v74, v75
	v_cvt_pk_bf16_f32 v81, v76, v77
	v_cvt_pk_bf16_f32 v86, v86, v87
	v_cvt_pk_bf16_f32 v87, v88, v89
	v_cvt_pk_bf16_f32 v88, v82, v83
	v_cvt_pk_bf16_f32 v89, v84, v85
	v_cvt_pk_bf16_f32 v70, v70, v71
	v_cvt_pk_bf16_f32 v71, v72, v73
	v_cvt_pk_bf16_f32 v72, v66, v67
	v_cvt_pk_bf16_f32 v73, v68, v69
	v_cvt_pk_bf16_f32 v62, v62, v63
	v_cvt_pk_bf16_f32 v63, v64, v65
	v_cvt_pk_bf16_f32 v64, v58, v59
	v_cvt_pk_bf16_f32 v65, v60, v61
	v_cvt_pk_bf16_f32 v46, v46, v47
	v_cvt_pk_bf16_f32 v47, v48, v49
	v_cvt_pk_bf16_f32 v48, v42, v43
	v_cvt_pk_bf16_f32 v49, v44, v45
	v_cvt_pk_bf16_f32 v54, v54, v55
	v_cvt_pk_bf16_f32 v55, v56, v57
	v_cvt_pk_bf16_f32 v56, v50, v51
	v_cvt_pk_bf16_f32 v57, v52, v53
	v_cvt_pk_bf16_f32 v30, v30, v31
	v_cvt_pk_bf16_f32 v31, v32, v33
	v_cvt_pk_bf16_f32 v32, v26, v27
	v_cvt_pk_bf16_f32 v33, v28, v29
	v_cvt_pk_bf16_f32 v38, v38, v39
	v_cvt_pk_bf16_f32 v39, v40, v41
	v_cvt_pk_bf16_f32 v40, v34, v35
	v_cvt_pk_bf16_f32 v41, v36, v37
	v_cvt_pk_bf16_f32 v14, v14, v15
	v_cvt_pk_bf16_f32 v15, v16, v17
	v_cvt_pk_bf16_f32 v16, v10, v11
	v_cvt_pk_bf16_f32 v17, v12, v13
	v_cvt_pk_bf16_f32 v22, v22, v23
	v_cvt_pk_bf16_f32 v23, v24, v25
	v_cvt_pk_bf16_f32 v24, v18, v19
	v_cvt_pk_bf16_f32 v25, v20, v21
	v_cvt_pk_bf16_f32 v6, v6, v7
	v_cvt_pk_bf16_f32 v7, v8, v9
	v_cvt_pk_bf16_f32 v8, v2, v3
	v_cvt_pk_bf16_f32 v9, v4, v5
	s_nop 1
	v_permlane16_swap_b32_e32 v126, v128
	v_permlane16_swap_b32_e32 v127, v129
	v_permlane16_swap_b32_e32 v110, v112
	v_permlane16_swap_b32_e32 v111, v113
	v_permlane16_swap_b32_e32 v118, v120
	v_permlane16_swap_b32_e32 v119, v121
	v_permlane16_swap_b32_e32 v94, v96
	v_permlane16_swap_b32_e32 v95, v97
	v_permlane16_swap_b32_e32 v102, v104
	v_permlane16_swap_b32_e32 v103, v105
	v_permlane16_swap_b32_e32 v78, v80
	v_permlane16_swap_b32_e32 v79, v81
	v_permlane16_swap_b32_e32 v86, v88
	v_permlane16_swap_b32_e32 v87, v89
	v_permlane16_swap_b32_e32 v70, v72
	v_permlane16_swap_b32_e32 v71, v73
	v_permlane16_swap_b32_e32 v62, v64
	v_permlane16_swap_b32_e32 v63, v65
	v_permlane16_swap_b32_e32 v46, v48
	v_permlane16_swap_b32_e32 v47, v49
	v_permlane16_swap_b32_e32 v54, v56
	v_permlane16_swap_b32_e32 v55, v57
	v_permlane16_swap_b32_e32 v30, v32
	v_permlane16_swap_b32_e32 v31, v33
	v_permlane16_swap_b32_e32 v38, v40
	v_permlane16_swap_b32_e32 v39, v41
	v_permlane16_swap_b32_e32 v14, v16
	v_permlane16_swap_b32_e32 v15, v17
	v_permlane16_swap_b32_e32 v22, v24
	v_permlane16_swap_b32_e32 v23, v25
	v_permlane16_swap_b32_e32 v6, v8
	v_permlane16_swap_b32_e32 v7, v9
	s_mov_b64 s[12:13], 0x10000
	global_store_dwordx4 v[146:147], v[126:129], off
	global_store_dwordx4 v[146:147], v[110:113], off offset:256
	v_lshl_add_u64 v[146:147], v[146:147], 0, s[12:13]
	global_store_dwordx4 v[146:147], v[118:121], off
	global_store_dwordx4 v[146:147], v[94:97], off offset:256
	v_lshl_add_u64 v[146:147], v[146:147], 0, s[12:13]
	global_store_dwordx4 v[146:147], v[102:105], off
	global_store_dwordx4 v[146:147], v[78:81], off offset:256
	v_lshl_add_u64 v[146:147], v[146:147], 0, s[12:13]
	global_store_dwordx4 v[146:147], v[86:89], off
	global_store_dwordx4 v[146:147], v[70:73], off offset:256
	s_mov_b64 s[12:13], 0x50000
	v_lshl_add_u64 v[146:147], v[146:147], 0, s[12:13]
	s_mov_b64 s[12:13], 0x10000
	global_store_dwordx4 v[146:147], v[62:65], off
	global_store_dwordx4 v[146:147], v[46:49], off offset:256
	v_lshl_add_u64 v[146:147], v[146:147], 0, s[12:13]
	global_store_dwordx4 v[146:147], v[54:57], off
	global_store_dwordx4 v[146:147], v[30:33], off offset:256
	v_lshl_add_u64 v[146:147], v[146:147], 0, s[12:13]
	global_store_dwordx4 v[146:147], v[38:41], off
	global_store_dwordx4 v[146:147], v[14:17], off offset:256
	v_lshl_add_u64 v[146:147], v[146:147], 0, s[12:13]
	global_store_dwordx4 v[146:147], v[22:25], off
	global_store_dwordx4 v[146:147], v[6:9], off offset:256
	s_nop 1
	s_cbranch_execz .LBB0_899

; __device__ __forceinline__ unsigned pk2(float lo, float hi) { f32x2 v = {lo, hi}; bf16x2_t b = __builtin_convertvector(v, bf16x2_t); return __builtin_bit_cast(unsigned, b); }
;     __device__ __forceinline__ void operator()(const f32x4 (&acc)[2][2][4][2], const Unit& u, int wr, int wc, int fr, int fq) const {
;     ...
; #pragma unroll
;             for (int ai = 0; ai < 2; ++ai)
; #pragma unroll
;                 for (int m = 0; m < 4; ++m) { bf16_t* rowp = Cb + (size_t)(row0 + ai * HALF + m * 16) * ldc + col0;
; #pragma unroll
;                     for (int bj = 0; bj < 2; ++bj)
; #pragma unroll
;                         for (int n = 0; n < 2; ++n) { const f32x4 v = acc[ai][bj][m][n]; *(u32x2*)(rowp + bj * HALF + n * 16) = (u32x2){pk2(v[0], v[1]), pk2(v[2], v[3])}; } }
.LBB0_1231:
	v_lshl_add_u32 v150, s14, 8, v142
	v_lshl_or_b32 v148, s41, 8, v144
	v_ashrrev_i32_e32 v151, 31, v150
	v_ashrrev_i32_e32 v149, 31, v148
	v_lshlrev_b64 v[152:153], 12, v[150:151]
	v_lshl_add_u64 v[152:153], s[86:87], 0, v[152:153]
	v_lshlrev_b64 v[148:149], 1, v[148:149]
	v_lshl_add_u64 v[152:153], v[152:153], 0, v[148:149]
	v_and_b32_e32 v148, 4, v144
	v_mul_u32_u24_e32 v148, 6, v148
	v_mov_b32_e32 v149, 0
	v_lshl_add_u64 v[152:153], v[152:153], 0, v[148:149]
	v_cvt_pk_bf16_f32 v126, v126, v127
	v_cvt_pk_bf16_f32 v127, v128, v129
	v_cvt_pk_bf16_f32 v128, v122, v123
	v_cvt_pk_bf16_f32 v129, v124, v125
	v_cvt_pk_bf16_f32 v114, v114, v115
	v_cvt_pk_bf16_f32 v115, v116, v117
	v_cvt_pk_bf16_f32 v116, v106, v107
	v_cvt_pk_bf16_f32 v117, v108, v109
	v_cvt_pk_bf16_f32 v118, v118, v119
	v_cvt_pk_bf16_f32 v119, v120, v121
	v_cvt_pk_bf16_f32 v120, v110, v111
	v_cvt_pk_bf16_f32 v121, v112, v113
	v_cvt_pk_bf16_f32 v98, v98, v99
	v_cvt_pk_bf16_f32 v99, v100, v101
	v_cvt_pk_bf16_f32 v100, v90, v91
	v_cvt_pk_bf16_f32 v101, v92, v93
	v_cvt_pk_bf16_f32 v102, v102, v103
	v_cvt_pk_bf16_f32 v103, v104, v105
	v_cvt_pk_bf16_f32 v104, v94, v95
	v_cvt_pk_bf16_f32 v105, v96, v97
	v_cvt_pk_bf16_f32 v82, v82, v83
	v_cvt_pk_bf16_f32 v83, v84, v85
	v_cvt_pk_bf16_f32 v84, v74, v75
	v_cvt_pk_bf16_f32 v85, v76, v77
	v_cvt_pk_bf16_f32 v86, v86, v87
	v_cvt_pk_bf16_f32 v87, v88, v89
	v_cvt_pk_bf16_f32 v88, v78, v79
	v_cvt_pk_bf16_f32 v89, v80, v81
	v_cvt_pk_bf16_f32 v70, v70, v71
	v_cvt_pk_bf16_f32 v71, v72, v73
	v_cvt_pk_bf16_f32 v72, v66, v67
	v_cvt_pk_bf16_f32 v73, v68, v69
	v_cvt_pk_bf16_f32 v62, v62, v63
	v_cvt_pk_bf16_f32 v63, v64, v65
	v_cvt_pk_bf16_f32 v64, v58, v59
	v_cvt_pk_bf16_f32 v65, v60, v61
	v_cvt_pk_bf16_f32 v50, v50, v51
	v_cvt_pk_bf16_f32 v51, v52, v53
	v_cvt_pk_bf16_f32 v52, v42, v43
	v_cvt_pk_bf16_f32 v53, v44, v45
	v_cvt_pk_bf16_f32 v54, v54, v55
	v_cvt_pk_bf16_f32 v55, v56, v57
	v_cvt_pk_bf16_f32 v56, v46, v47
	v_cvt_pk_bf16_f32 v57, v48, v49
	v_cvt_pk_bf16_f32 v34, v34, v35
	v_cvt_pk_bf16_f32 v35, v36, v37
	v_cvt_pk_bf16_f32 v36, v26, v27
	v_cvt_pk_bf16_f32 v37, v28, v29
	v_cvt_pk_bf16_f32 v38, v38, v39
	v_cvt_pk_bf16_f32 v39, v40, v41
	v_cvt_pk_bf16_f32 v40, v30, v31
	v_cvt_pk_bf16_f32 v41, v32, v33
	v_cvt_pk_bf16_f32 v18, v18, v19
	v_cvt_pk_bf16_f32 v19, v20, v21
	v_cvt_pk_bf16_f32 v20, v10, v11
	v_cvt_pk_bf16_f32 v21, v12, v13
	v_cvt_pk_bf16_f32 v22, v22, v23
	v_cvt_pk_bf16_f32 v23, v24, v25
	v_cvt_pk_bf16_f32 v24, v14, v15
	v_cvt_pk_bf16_f32 v25, v16, v17
	v_cvt_pk_bf16_f32 v6, v6, v7
	v_cvt_pk_bf16_f32 v7, v8, v9
	v_cvt_pk_bf16_f32 v8, v2, v3
	v_cvt_pk_bf16_f32 v9, v4, v5
	s_nop 1
	v_permlane16_swap_b32_e32 v126, v128
	v_permlane16_swap_b32_e32 v127, v129
	v_permlane16_swap_b32_e32 v114, v116
	v_permlane16_swap_b32_e32 v115, v117
	v_permlane16_swap_b32_e32 v118, v120
	v_permlane16_swap_b32_e32 v119, v121
	v_permlane16_swap_b32_e32 v98, v100
	v_permlane16_swap_b32_e32 v99, v101
	v_permlane16_swap_b32_e32 v102, v104
	v_permlane16_swap_b32_e32 v103, v105
	v_permlane16_swap_b32_e32 v82, v84
	v_permlane16_swap_b32_e32 v83, v85
	v_permlane16_swap_b32_e32 v86, v88
	v_permlane16_swap_b32_e32 v87, v89
	v_permlane16_swap_b32_e32 v70, v72
	v_permlane16_swap_b32_e32 v71, v73
	v_permlane16_swap_b32_e32 v62, v64
	v_permlane16_swap_b32_e32 v63, v65
	v_permlane16_swap_b32_e32 v50, v52
	v_permlane16_swap_b32_e32 v51, v53
	v_permlane16_swap_b32_e32 v54, v56
	v_permlane16_swap_b32_e32 v55, v57
	v_permlane16_swap_b32_e32 v34, v36
	v_permlane16_swap_b32_e32 v35, v37
	v_permlane16_swap_b32_e32 v38, v40
	v_permlane16_swap_b32_e32 v39, v41
	v_permlane16_swap_b32_e32 v18, v20
	v_permlane16_swap_b32_e32 v19, v21
	v_permlane16_swap_b32_e32 v22, v24
	v_permlane16_swap_b32_e32 v23, v25
	v_permlane16_swap_b32_e32 v6, v8
	v_permlane16_swap_b32_e32 v7, v9
	s_mov_b64 s[6:7], 0x10000
	global_store_dwordx4 v[152:153], v[126:129], off
	global_store_dwordx4 v[152:153], v[114:117], off offset:256
	v_lshl_add_u64 v[152:153], v[152:153], 0, s[6:7]
	global_store_dwordx4 v[152:153], v[118:121], off
	global_store_dwordx4 v[152:153], v[98:101], off offset:256
	v_lshl_add_u64 v[152:153], v[152:153], 0, s[6:7]
	global_store_dwordx4 v[152:153], v[102:105], off
	global_store_dwordx4 v[152:153], v[82:85], off offset:256
	v_lshl_add_u64 v[152:153], v[152:153], 0, s[6:7]
	global_store_dwordx4 v[152:153], v[86:89], off
	global_store_dwordx4 v[152:153], v[70:73], off offset:256
	s_mov_b64 s[6:7], 0x50000
	v_lshl_add_u64 v[152:153], v[152:153], 0, s[6:7]
	s_mov_b64 s[6:7], 0x10000
	global_store_dwordx4 v[152:153], v[62:65], off
	global_store_dwordx4 v[152:153], v[50:53], off offset:256
	v_lshl_add_u64 v[152:153], v[152:153], 0, s[6:7]
	global_store_dwordx4 v[152:153], v[54:57], off
	global_store_dwordx4 v[152:153], v[34:37], off offset:256
	v_lshl_add_u64 v[152:153], v[152:153], 0, s[6:7]
	global_store_dwordx4 v[152:153], v[38:41], off
	global_store_dwordx4 v[152:153], v[18:21], off offset:256
	v_lshl_add_u64 v[152:153], v[152:153], 0, s[6:7]
	global_store_dwordx4 v[152:153], v[22:25], off
	global_store_dwordx4 v[152:153], v[6:9], off offset:256
	s_andn2_b64 vcc, exec, s[0:1]
	s_mov_b64 s[0:1], -1
	s_nop 0
	s_cbranch_vccnz .LBB0_1224
	s_andn2_b64 vcc, exec, s[4:5]
	s_cbranch_vccnz .LBB0_1223
	s_barrier
	s_branch .LBB0_1223

; __device__ __forceinline__ unsigned pk2(float lo, float hi) { f32x2 v = {lo, hi}; bf16x2_t b = __builtin_convertvector(v, bf16x2_t); return __builtin_bit_cast(unsigned, b); }
;     __device__ __forceinline__ void operator()(const f32x4 (&acc)[2][2][4][2], const Unit& u, int wr, int wc, int fr, int fq) const {
;     ...
; #pragma unroll
;             for (int ai = 0; ai < 2; ++ai)
; #pragma unroll
;                 for (int m = 0; m < 4; ++m) { bf16_t* rowp = Cb + (size_t)(row0 + ai * HALF + m * 16) * ldc + col0;
; #pragma unroll
;                     for (int bj = 0; bj < 2; ++bj)
; #pragma unroll
;                         for (int n = 0; n < 2; ++n) { const f32x4 v = acc[ai][bj][m][n]; *(u32x2*)(rowp + bj * HALF + n * 16) = (u32x2){pk2(v[0], v[1]), pk2(v[2], v[3])}; } }
.LBB0_1535:
	v_lshl_add_u32 v136, s58, 8, v140
	v_lshl_or_b32 v138, s57, 8, v142
	s_mov_b64 s[30:31], -1
	s_cmp_gt_i32 s4, -1
	v_ashrrev_i32_e32 v139, 31, v138
	v_ashrrev_i32_e32 v137, 31, v136
	s_cbranch_scc1 .LBB0_1540
	v_lshlrev_b64 v[146:147], 12, v[136:137]
	v_lshl_add_u64 v[146:147], s[86:87], 0, v[146:147]
	v_lshlrev_b64 v[148:149], 1, v[138:139]
	v_lshl_add_u64 v[146:147], v[146:147], 0, v[148:149]
	v_and_b32_e32 v148, 4, v142
	v_mul_u32_u24_e32 v148, 6, v148
	v_mov_b32_e32 v149, 0
	v_lshl_add_u64 v[146:147], v[146:147], 0, v[148:149]
	v_cvt_pk_bf16_f32 v126, v126, v127
	v_cvt_pk_bf16_f32 v127, v128, v129
	v_cvt_pk_bf16_f32 v128, v122, v123
	v_cvt_pk_bf16_f32 v129, v124, v125
	v_cvt_pk_bf16_f32 v110, v110, v111
	v_cvt_pk_bf16_f32 v111, v112, v113
	v_cvt_pk_bf16_f32 v112, v106, v107
	v_cvt_pk_bf16_f32 v113, v108, v109
	v_cvt_pk_bf16_f32 v118, v118, v119
	v_cvt_pk_bf16_f32 v119, v120, v121
	v_cvt_pk_bf16_f32 v120, v114, v115
	v_cvt_pk_bf16_f32 v121, v116, v117
	v_cvt_pk_bf16_f32 v94, v94, v95
	v_cvt_pk_bf16_f32 v95, v96, v97
	v_cvt_pk_bf16_f32 v96, v86, v87
	v_cvt_pk_bf16_f32 v97, v88, v89
	v_cvt_pk_bf16_f32 v102, v102, v103
	v_cvt_pk_bf16_f32 v103, v104, v105
	v_cvt_pk_bf16_f32 v104, v98, v99
	v_cvt_pk_bf16_f32 v105, v100, v101
	v_cvt_pk_bf16_f32 v78, v78, v79
	v_cvt_pk_bf16_f32 v79, v80, v81
	v_cvt_pk_bf16_f32 v80, v74, v75
	v_cvt_pk_bf16_f32 v81, v76, v77
	v_cvt_pk_bf16_f32 v90, v90, v91
	v_cvt_pk_bf16_f32 v91, v92, v93
	v_cvt_pk_bf16_f32 v92, v82, v83
	v_cvt_pk_bf16_f32 v93, v84, v85
	v_cvt_pk_bf16_f32 v70, v70, v71
	v_cvt_pk_bf16_f32 v71, v72, v73
	v_cvt_pk_bf16_f32 v72, v66, v67
	v_cvt_pk_bf16_f32 v73, v68, v69
	v_cvt_pk_bf16_f32 v62, v62, v63
	v_cvt_pk_bf16_f32 v63, v64, v65
	v_cvt_pk_bf16_f32 v64, v58, v59
	v_cvt_pk_bf16_f32 v65, v60, v61
	v_cvt_pk_bf16_f32 v46, v46, v47
	v_cvt_pk_bf16_f32 v47, v48, v49
	v_cvt_pk_bf16_f32 v48, v38, v39
	v_cvt_pk_bf16_f32 v49, v40, v41
	v_cvt_pk_bf16_f32 v54, v54, v55
	v_cvt_pk_bf16_f32 v55, v56, v57
	v_cvt_pk_bf16_f32 v56, v50, v51
	v_cvt_pk_bf16_f32 v57, v52, v53
	v_cvt_pk_bf16_f32 v30, v30, v31
	v_cvt_pk_bf16_f32 v31, v32, v33
	v_cvt_pk_bf16_f32 v32, v22, v23
	v_cvt_pk_bf16_f32 v33, v24, v25
	v_cvt_pk_bf16_f32 v42, v42, v43
	v_cvt_pk_bf16_f32 v43, v44, v45
	v_cvt_pk_bf16_f32 v44, v34, v35
	v_cvt_pk_bf16_f32 v45, v36, v37
	v_cvt_pk_bf16_f32 v14, v14, v15
	v_cvt_pk_bf16_f32 v15, v16, v17
	v_cvt_pk_bf16_f32 v16, v10, v11
	v_cvt_pk_bf16_f32 v17, v12, v13
	v_cvt_pk_bf16_f32 v26, v26, v27
	v_cvt_pk_bf16_f32 v27, v28, v29
	v_cvt_pk_bf16_f32 v28, v18, v19
	v_cvt_pk_bf16_f32 v29, v20, v21
	v_cvt_pk_bf16_f32 v6, v6, v7
	v_cvt_pk_bf16_f32 v7, v8, v9
	v_cvt_pk_bf16_f32 v8, v2, v3
	v_cvt_pk_bf16_f32 v9, v4, v5
	s_nop 1
	v_permlane16_swap_b32_e32 v126, v128
	v_permlane16_swap_b32_e32 v127, v129
	v_permlane16_swap_b32_e32 v110, v112
	v_permlane16_swap_b32_e32 v111, v113
	v_permlane16_swap_b32_e32 v118, v120
	v_permlane16_swap_b32_e32 v119, v121
	v_permlane16_swap_b32_e32 v94, v96
	v_permlane16_swap_b32_e32 v95, v97
	v_permlane16_swap_b32_e32 v102, v104
	v_permlane16_swap_b32_e32 v103, v105
	v_permlane16_swap_b32_e32 v78, v80
	v_permlane16_swap_b32_e32 v79, v81
	v_permlane16_swap_b32_e32 v90, v92
	v_permlane16_swap_b32_e32 v91, v93
	v_permlane16_swap_b32_e32 v70, v72
	v_permlane16_swap_b32_e32 v71, v73
	v_permlane16_swap_b32_e32 v62, v64
	v_permlane16_swap_b32_e32 v63, v65
	v_permlane16_swap_b32_e32 v46, v48
	v_permlane16_swap_b32_e32 v47, v49
	v_permlane16_swap_b32_e32 v54, v56
	v_permlane16_swap_b32_e32 v55, v57
	v_permlane16_swap_b32_e32 v30, v32
	v_permlane16_swap_b32_e32 v31, v33
	v_permlane16_swap_b32_e32 v42, v44
	v_permlane16_swap_b32_e32 v43, v45
	v_permlane16_swap_b32_e32 v14, v16
	v_permlane16_swap_b32_e32 v15, v17
	v_permlane16_swap_b32_e32 v26, v28
	v_permlane16_swap_b32_e32 v27, v29
	v_permlane16_swap_b32_e32 v6, v8
	v_permlane16_swap_b32_e32 v7, v9
	s_mov_b64 s[30:31], 0x10000
	global_store_dwordx4 v[146:147], v[126:129], off
	global_store_dwordx4 v[146:147], v[110:113], off offset:256
	v_lshl_add_u64 v[146:147], v[146:147], 0, s[30:31]
	global_store_dwordx4 v[146:147], v[118:121], off
	global_store_dwordx4 v[146:147], v[94:97], off offset:256
	v_lshl_add_u64 v[146:147], v[146:147], 0, s[30:31]
	global_store_dwordx4 v[146:147], v[102:105], off
	global_store_dwordx4 v[146:147], v[78:81], off offset:256
	v_lshl_add_u64 v[146:147], v[146:147], 0, s[30:31]
	global_store_dwordx4 v[146:147], v[90:93], off
	global_store_dwordx4 v[146:147], v[70:73], off offset:256
	s_mov_b64 s[30:31], 0x50000
	v_lshl_add_u64 v[146:147], v[146:147], 0, s[30:31]
	s_mov_b64 s[30:31], 0x10000
	global_store_dwordx4 v[146:147], v[62:65], off
	global_store_dwordx4 v[146:147], v[46:49], off offset:256
	v_lshl_add_u64 v[146:147], v[146:147], 0, s[30:31]
	global_store_dwordx4 v[146:147], v[54:57], off
	global_store_dwordx4 v[146:147], v[30:33], off offset:256
	v_lshl_add_u64 v[146:147], v[146:147], 0, s[30:31]
	global_store_dwordx4 v[146:147], v[42:45], off
	global_store_dwordx4 v[146:147], v[14:17], off offset:256
	v_lshl_add_u64 v[146:147], v[146:147], 0, s[30:31]
	global_store_dwordx4 v[146:147], v[26:29], off
	global_store_dwordx4 v[146:147], v[6:9], off offset:256
	s_nop 1
	s_cbranch_execz .LBB0_1541
